# g1_throttle_3us_with_hand_scheduled_scan
# baseline (speedup 1.0000x reference)
.LBB0_2357:
	s_or_b64 exec, exec, s[0:1]
	s_add_i32 s91, s42, s91
	s_cmpk_lt_i32 s91, 0xc00
	s_cbranch_scc0 .LBB0_2485
	s_sleep 96
